# selected-block attention pass: per-lane selection mask written straight into the softmax input registers (17 staging register copies per tile removed)
# baseline (speedup 1.0000x reference)
.LBB0_957:
	s_cmp_lg_u64 s[16:17], exec
	s_cbranch_scc0 .LBB0_959
	s_nop 0
	v_cndmask_b32_e64 v96, v244, v64, s[16:17]
	v_cndmask_b32_e64 v80, v244, v80, s[16:17]
	v_cndmask_b32_e64 v97, v244, v65, s[16:17]
	v_cndmask_b32_e64 v81, v244, v81, s[16:17]
	v_cndmask_b32_e64 v98, v244, v66, s[16:17]
	v_cndmask_b32_e64 v82, v244, v82, s[16:17]
	v_cndmask_b32_e64 v99, v244, v67, s[16:17]
	v_cndmask_b32_e64 v83, v244, v83, s[16:17]
	v_cndmask_b32_e64 v100, v244, v68, s[16:17]
	v_cndmask_b32_e64 v84, v244, v84, s[16:17]
	v_cndmask_b32_e64 v101, v244, v69, s[16:17]
	v_cndmask_b32_e64 v85, v244, v85, s[16:17]
	v_cndmask_b32_e64 v102, v244, v70, s[16:17]
	v_cndmask_b32_e64 v86, v244, v86, s[16:17]
	v_cndmask_b32_e64 v103, v244, v71, s[16:17]
	v_cndmask_b32_e64 v87, v244, v87, s[16:17]
	v_cndmask_b32_e64 v104, v244, v72, s[16:17]
	v_cndmask_b32_e64 v88, v244, v88, s[16:17]
	v_cndmask_b32_e64 v105, v244, v73, s[16:17]
	v_cndmask_b32_e64 v89, v244, v89, s[16:17]
	v_cndmask_b32_e64 v106, v244, v74, s[16:17]
	v_cndmask_b32_e64 v90, v244, v90, s[16:17]
	v_cndmask_b32_e64 v107, v244, v75, s[16:17]
	v_cndmask_b32_e64 v91, v244, v91, s[16:17]
	v_cndmask_b32_e64 v108, v244, v76, s[16:17]
	v_cndmask_b32_e64 v92, v244, v92, s[16:17]
	v_cndmask_b32_e64 v109, v244, v77, s[16:17]
	v_cndmask_b32_e64 v93, v244, v93, s[16:17]
	v_cndmask_b32_e64 v110, v244, v78, s[16:17]
	v_cndmask_b32_e64 v94, v244, v94, s[16:17]
	v_cndmask_b32_e64 v111, v244, v79, s[16:17]
	v_cndmask_b32_e64 v95, v244, v95, s[16:17]
	s_branch .LBB0_962

.LBB0_977:
	s_cmp_lg_u64 s[16:17], exec
	s_cbranch_scc0 .LBB0_979
	s_nop 0
	v_cndmask_b32_e64 v80, v244, v96, s[16:17]
	v_cndmask_b32_e64 v64, v244, v64, s[16:17]
	v_cndmask_b32_e64 v81, v244, v97, s[16:17]
	v_cndmask_b32_e64 v65, v244, v65, s[16:17]
	v_cndmask_b32_e64 v82, v244, v98, s[16:17]
	v_cndmask_b32_e64 v66, v244, v66, s[16:17]
	v_cndmask_b32_e64 v83, v244, v99, s[16:17]
	v_cndmask_b32_e64 v67, v244, v67, s[16:17]
	v_cndmask_b32_e64 v84, v244, v100, s[16:17]
	v_cndmask_b32_e64 v68, v244, v68, s[16:17]
	v_cndmask_b32_e64 v85, v244, v101, s[16:17]
	v_cndmask_b32_e64 v69, v244, v69, s[16:17]
	v_cndmask_b32_e64 v86, v244, v102, s[16:17]
	v_cndmask_b32_e64 v70, v244, v70, s[16:17]
	v_cndmask_b32_e64 v87, v244, v103, s[16:17]
	v_cndmask_b32_e64 v71, v244, v71, s[16:17]
	v_cndmask_b32_e64 v88, v244, v104, s[16:17]
	v_cndmask_b32_e64 v72, v244, v72, s[16:17]
	v_cndmask_b32_e64 v89, v244, v105, s[16:17]
	v_cndmask_b32_e64 v73, v244, v73, s[16:17]
	v_cndmask_b32_e64 v90, v244, v106, s[16:17]
	v_cndmask_b32_e64 v74, v244, v74, s[16:17]
	v_cndmask_b32_e64 v91, v244, v107, s[16:17]
	v_cndmask_b32_e64 v75, v244, v75, s[16:17]
	v_cndmask_b32_e64 v92, v244, v108, s[16:17]
	v_cndmask_b32_e64 v76, v244, v76, s[16:17]
	v_cndmask_b32_e64 v93, v244, v109, s[16:17]
	v_cndmask_b32_e64 v77, v244, v77, s[16:17]
	v_cndmask_b32_e64 v94, v244, v110, s[16:17]
	v_cndmask_b32_e64 v78, v244, v78, s[16:17]
	v_cndmask_b32_e64 v95, v244, v111, s[16:17]
	v_cndmask_b32_e64 v79, v244, v79, s[16:17]
	s_branch .LBB0_982
